# P2 K-loop: each workgroup barrier taken by one half only (leading half behind its MFMA blocks, trailing half behind its reads); prologue offset, epilogue alignment and restore barriers removed; on top
# baseline (speedup 1.0000x reference)
.LBB0_203:
	s_add_u32 s38, s62, 0x36c00000
	s_addc_u32 s39, s63, 0
	v_readlane_b32 s2, v255, 3
	v_readlane_b32 s3, v255, 4
	s_cmp_lt_i32 s2, 3
	s_cselect_b64 s[0:1], -1, 0
	s_cmp_gt_i32 s3, 2
	s_cselect_b64 s[2:3], -1, 0
	s_and_b64 s[0:1], s[0:1], s[2:3]
	s_andn2_b64 vcc, exec, s[0:1]
	s_cbranch_vccnz .LBB0_273
	s_cmpk_gt_i32 s10, 0x2aff
	v_readfirstlane_b32 s3, v0
	s_cbranch_scc1 .LBB0_220
	v_lshrrev_b32_e32 v1, 5, v0
	v_lshrrev_b32_e32 v3, 1, v0
	v_and_b32_e32 v1, 4, v1
	v_bfe_u32 v2, v0, 2, 2
	v_and_b32_e32 v13, 24, v3
	v_or3_b32 v1, v1, v2, v13
	v_lshlrev_b32_e32 v2, 4, v0
	v_or_b32_e32 v10, 0x2000, v2
	v_lshrrev_b32_e32 v3, 7, v10
	s_movk_i32 s0, 0x60
	v_and_or_b32 v4, v3, s0, v1
	v_bfe_u32 v14, v0, 2, 4
	s_movk_i32 s0, 0x70
	s_ashr_i32 s41, s10, 31
	v_and_or_b32 v3, v3, s0, v14
	s_lshr_b32 s0, s41, 29
	s_add_i32 s0, s10, s0
	s_lshr_b32 s4, s3, 6
	s_ashr_i32 s1, s0, 3
	s_and_b32 s0, s0, -8
	s_lshr_b32 s6, s3, 8
	s_lshl_b32 s35, s4, 10
	s_sub_i32 s0, s10, s0
	s_cmp_lt_i32 s0, 0
	s_movk_i32 s56, 0x561
	s_cselect_b32 s2, s56, 0x560
	s_mul_i32 s0, s0, s2
	s_add_i32 s0, s0, s1
	s_mul_hi_i32 s1, s0, 0x2fa0be83
	s_lshr_b32 s2, s1, 31
	s_ashr_i32 s1, s1, 7
	s_add_i32 s1, s1, s2
	s_lshl_b32 s5, s1, 3
	s_mulk_i32 s1, 0x2b0
	s_sub_i32 s0, s0, s1
	s_sext_i32_i16 s1, s0
	s_bfe_u32 s1, s1, 0x3001c
	s_add_i32 s1, s0, s1
	s_sext_i32_i16 s2, s1
	s_and_b32 s1, s1, 0xfff8
	s_sub_i32 s0, s0, s1
	s_sext_i32_i16 s0, s0
	v_and_b32_e32 v5, 32, v0
	s_lshr_b32 s2, s2, 3
	s_add_i32 s82, s5, s0
	v_bitop3_b32 v11, v2, v5, 48 bitop3:0x6c
	v_and_b32_e32 v12, 64, v0
	s_ashr_i32 s83, s82, 31
	s_bfe_i64 s[8:9], s[2:3], 0x100000
	v_or_b32_e32 v2, v11, v12
	s_lshl_b64 s[0:1], s[82:83], 20
	s_lshl_b64 s[8:9], s[8:9], 20
	v_lshl_or_b32 v132, v3, 12, v2
	v_lshrrev_b32_e32 v3, 3, v0
	s_add_u32 s86, s14, s8
	v_and_or_b32 v1, v3, 32, v1
	s_addc_u32 s87, s15, s9
	s_add_i32 s57, s35, 0
	v_lshl_or_b32 v134, v1, 12, v2
	s_add_i32 m0, s57, 0x10000
	v_lshl_or_b32 v130, v4, 12, v2
	global_load_lds_dwordx4 v134, s[86:87]
	s_add_i32 m0, s57, 0x12000
	s_add_u32 s8, s86, 0x80000
	global_load_lds_dwordx4 v130, s[86:87]
	s_addc_u32 s9, s87, 0
	s_add_i32 m0, s57, 0x14000
	v_and_or_b32 v1, v3, 48, v14
	global_load_lds_dwordx4 v134, s[8:9]
	s_add_i32 m0, s57, 0x16000
	s_add_u32 s84, s30, s0
	s_addc_u32 s85, s31, s1
	s_add_i32 s58, s57, 0x2000
	v_lshl_or_b32 v136, v1, 12, v2
	global_load_lds_dwordx4 v130, s[8:9]
	s_mov_b32 m0, s57
	s_add_u32 s0, s84, 0x80000
	global_load_lds_dwordx4 v136, s[84:85]
	s_mov_b32 m0, s58
	s_addc_u32 s1, s85, 0
	s_add_i32 s59, s57, 0x4000
	global_load_lds_dwordx4 v132, s[84:85]
	s_mov_b32 m0, s59
	s_add_i32 s61, s57, 0x6000
	global_load_lds_dwordx4 v136, s[0:1]
	s_mov_b32 m0, s61
	v_mov_b32_e32 v135, 0
	global_load_lds_dwordx4 v132, s[0:1]
	v_mov_b32_e32 v131, v135
	v_mov_b32_e32 v137, v135
	v_mov_b32_e32 v133, v135
	s_cmp_eq_u32 s6, 1
	s_mov_b32 s66, 0
	v_lshl_add_u64 v[8:9], s[86:87], 0, v[134:135]
	v_lshl_add_u64 v[6:7], s[86:87], 0, v[130:131]
	v_lshl_add_u64 v[2:3], s[84:85], 0, v[136:137]
	s_cselect_b64 s[0:1], -1, 0
	s_cmp_lg_u32 s6, 1
	v_lshl_add_u64 v[4:5], s[84:85], 0, v[132:133]
	s_cbranch_scc1 .LBB0_207
.LBB0_207:
	s_lshl_b32 s4, s4, 5
	s_and_b32 s12, s4, 0x60
	s_mov_b64 s[4:5], 0x80
	s_add_i32 m0, s57, 0x18000
	v_lshl_add_u64 v[8:9], v[8:9], 0, s[4:5]
	s_lshl_b32 s7, s6, 13
	s_lshl_b32 s13, s12, 7
	s_waitcnt vmcnt(2)
	s_barrier
	global_load_lds_dwordx4 v[8:9], off
	v_lshl_add_u64 v[6:7], v[6:7], 0, s[4:5]
	s_add_i32 m0, s57, 0x1a000
	s_add_i32 s67, s57, 0x8000
	s_add_i32 s68, s57, 0xa000
	global_load_lds_dwordx4 v[6:7], off
	v_lshl_add_u64 v[2:3], v[2:3], 0, s[4:5]
	s_mov_b32 m0, s67
	s_add_u32 s8, s86, 0x80080
	global_load_lds_dwordx4 v[2:3], off
	v_lshl_add_u64 v[2:3], v[4:5], 0, s[4:5]
	s_mov_b32 m0, s68
	s_addc_u32 s9, s87, 0
	global_load_lds_dwordx4 v[2:3], off
	s_add_i32 m0, s57, 0x1c000
	v_lshl_add_u64 v[2:3], s[8:9], 0, v[134:135]
	global_load_lds_dwordx4 v[2:3], off
	v_lshl_add_u64 v[2:3], s[8:9], 0, v[130:131]
	s_add_i32 m0, s57, 0x1e000
	s_sext_i32_i16 s92, s2
	global_load_lds_dwordx4 v[2:3], off
	v_and_b32_e32 v2, 15, v0
	v_lshlrev_b32_e32 v3, 1, v13
	v_lshlrev_b32_e32 v4, 2, v0
	v_lshlrev_b32_e32 v5, 6, v0
	s_movk_i32 s2, 0x3c0
	v_lshl_or_b32 v1, s6, 6, v2
	v_lshl_or_b32 v2, v2, 6, v3
	v_and_b32_e32 v4, 32, v4
	v_and_or_b32 v3, v5, s2, v3
	v_bitop3_b32 v154, s13, v3, v4 bitop3:0xf6
	v_lshlrev_b32_e32 v3, 9, v0
	v_bitop3_b32 v2, v2, s7, v4 bitop3:0xde
	v_and_b32_e32 v3, 0x30000, v3
	v_lshlrev_b32_e32 v4, 12, v14
	s_cmpk_lt_u32 s3, 0x100
	v_or3_b32 v3, v11, v3, v4
	s_cselect_b64 s[6:7], -1, 0
	s_ashr_i32 s69, s11, 31
	v_add_u32_e32 v138, v3, v12
	v_lshlrev_b32_e32 v3, 5, v10
	s_waitcnt vmcnt(6)
	s_add_u32 s36, s62, 0x34400
	v_and_b32_e32 v3, 0x70000, v3
	s_addc_u32 s37, s63, 0
	v_or3_b32 v3, v11, v3, v4
	s_add_i32 s83, 0, 0x10000
	s_add_i32 s90, 0, 0x14000
	v_or_b32_e32 v155, s12, v13
	v_mov_b32_e32 v139, v135
	v_add_u32_e32 v140, v3, v12
	v_mov_b32_e32 v141, v135
	v_mov_b64_e32 v[142:143], 0x2b00
	v_mov_b64_e32 v[144:145], 0x2aff
	v_add_u32_e32 v156, s83, v154
	v_add_u32_e32 v157, s90, v154
	v_add_u32_e32 v158, 0, v2
	s_mov_b32 s40, 0x3c010204
	s_movk_i32 s91, 0x5600
	s_barrier
	s_branch .LBB0_210

.LBB0_213:
	s_and_b64 vcc, exec, s[6:7]
	ds_read_b128 v[146:149], v156
	ds_read_b128 v[150:153], v156 offset:1024
	ds_read_b128 v[160:163], v156 offset:2048
	ds_read_b128 v[164:167], v156 offset:3072
	ds_read_b128 v[168:171], v157
	ds_read_b128 v[172:175], v157 offset:1024
	ds_read_b128 v[176:179], v157 offset:2048
	ds_read_b128 v[180:183], v157 offset:3072
	s_add_u32 s19, s84, 0xfff80080
	s_addc_u32 s20, s85, -1
	s_cmp_eq_u32 s18, 28
	s_cselect_b32 s89, s8, s20
	s_cselect_b32 s88, s9, s19
	s_cselect_b32 s87, s12, s17
	s_cselect_b32 s86, s13, s16
	v_lshl_add_u64 v[216:217], s[84:85], 0, v[138:139]
	s_add_i32 m0, s57, 0xc000
	ds_read_b128 v[184:187], v158
	ds_read_b128 v[188:191], v158 offset:1024
	ds_read_b128 v[192:195], v158 offset:2048
	ds_read_b128 v[196:199], v158 offset:3072
	ds_read_b128 v[200:203], v158 offset:4096
	ds_read_b128 v[204:207], v158 offset:5120
	ds_read_b128 v[208:211], v158 offset:6144
	ds_read_b128 v[212:215], v158 offset:7168
	global_load_lds_dwordx4 v[216:217], off
	v_lshl_add_u64 v[216:217], s[84:85], 0, v[140:141]
	s_add_i32 m0, s57, 0xe000
	s_nop 0
	global_load_lds_dwordx4 v[216:217], off
	s_waitcnt vmcnt(8)
	s_waitcnt lgkmcnt(0)
	s_cbranch_vccnz .Lhb_p2_0
	s_barrier
.Lhb_p2_0:
	s_setprio 1
	s_waitcnt lgkmcnt(0)
	v_mfma_i32_16x16x64_i8 v[126:129], v[146:149], v[184:187], v[126:129]
	v_mfma_i32_16x16x64_i8 v[122:125], v[160:163], v[184:187], v[122:125]
	v_mfma_i32_16x16x64_i8 v[110:113], v[146:149], v[192:195], v[110:113]
	v_mfma_i32_16x16x64_i8 v[106:109], v[160:163], v[192:195], v[106:109]
	v_mfma_i32_16x16x64_i8 v[94:97], v[146:149], v[200:203], v[94:97]
	v_mfma_i32_16x16x64_i8 v[90:93], v[160:163], v[200:203], v[90:93]
	v_mfma_i32_16x16x64_i8 v[78:81], v[146:149], v[208:211], v[78:81]
	v_mfma_i32_16x16x64_i8 v[74:77], v[160:163], v[208:211], v[74:77]
	v_mfma_i32_16x16x64_i8 v[126:129], v[150:153], v[188:191], v[126:129]
	v_mfma_i32_16x16x64_i8 v[122:125], v[164:167], v[188:191], v[122:125]
	v_mfma_i32_16x16x64_i8 v[110:113], v[150:153], v[196:199], v[110:113]
	v_mfma_i32_16x16x64_i8 v[106:109], v[164:167], v[196:199], v[106:109]
	v_mfma_i32_16x16x64_i8 v[94:97], v[150:153], v[204:207], v[94:97]
	v_mfma_i32_16x16x64_i8 v[90:93], v[164:167], v[204:207], v[90:93]
	v_mfma_i32_16x16x64_i8 v[78:81], v[150:153], v[212:215], v[78:81]
	v_mfma_i32_16x16x64_i8 v[74:77], v[164:167], v[212:215], v[74:77]
	s_setprio 0
	s_setprio 1
	v_mfma_i32_16x16x64_i8 v[118:121], v[168:171], v[184:187], v[118:121]
	v_mfma_i32_16x16x64_i8 v[114:117], v[176:179], v[184:187], v[114:117]
	v_mfma_i32_16x16x64_i8 v[102:105], v[168:171], v[192:195], v[102:105]
	v_mfma_i32_16x16x64_i8 v[98:101], v[176:179], v[192:195], v[98:101]
	v_mfma_i32_16x16x64_i8 v[86:89], v[168:171], v[200:203], v[86:89]
	v_mfma_i32_16x16x64_i8 v[82:85], v[176:179], v[200:203], v[82:85]
	v_mfma_i32_16x16x64_i8 v[70:73], v[168:171], v[208:211], v[70:73]
	v_mfma_i32_16x16x64_i8 v[66:69], v[176:179], v[208:211], v[66:69]
	v_mfma_i32_16x16x64_i8 v[118:121], v[172:175], v[188:191], v[118:121]
	v_mfma_i32_16x16x64_i8 v[114:117], v[180:183], v[188:191], v[114:117]
	v_mfma_i32_16x16x64_i8 v[102:105], v[172:175], v[196:199], v[102:105]
	v_mfma_i32_16x16x64_i8 v[98:101], v[180:183], v[196:199], v[98:101]
	v_mfma_i32_16x16x64_i8 v[86:89], v[172:175], v[204:207], v[86:89]
	v_mfma_i32_16x16x64_i8 v[82:85], v[180:183], v[204:207], v[82:85]
	v_mfma_i32_16x16x64_i8 v[70:73], v[172:175], v[212:215], v[70:73]
	v_mfma_i32_16x16x64_i8 v[66:69], v[180:183], v[212:215], v[66:69]
	s_setprio 0
	s_cbranch_vccz .Lhb_p2_1
	s_barrier
.Lhb_p2_1:
	s_add_i32 s19, s83, s35
	v_lshl_add_u64 v[216:217], s[86:87], 0, v[134:135]
	s_mov_b32 m0, s19
	ds_read_b128 v[184:187], v158 offset:16384
	ds_read_b128 v[188:191], v158 offset:17408
	ds_read_b128 v[192:195], v158 offset:18432
	ds_read_b128 v[196:199], v158 offset:19456
	ds_read_b128 v[200:203], v158 offset:20480
	ds_read_b128 v[204:207], v158 offset:21504
	ds_read_b128 v[208:211], v158 offset:22528
	ds_read_b128 v[212:215], v158 offset:23552
	global_load_lds_dwordx4 v[216:217], off
	s_add_i32 m0, s19, 0x2000
	s_add_u32 s20, s86, 0x80000
	v_lshl_add_u64 v[218:219], s[86:87], 0, v[130:131]
	s_addc_u32 s21, s87, 0
	s_add_i32 s19, s90, s35
	global_load_lds_dwordx4 v[218:219], off
	v_lshl_add_u64 v[220:221], s[20:21], 0, v[134:135]
	s_mov_b32 m0, s19
	v_lshl_add_u64 v[222:223], s[88:89], 0, v[132:133]
	global_load_lds_dwordx4 v[220:221], off
	v_lshl_add_u64 v[220:221], s[20:21], 0, v[130:131]
	s_add_i32 m0, s19, 0x2000
	s_nop 0
	global_load_lds_dwordx4 v[220:221], off
	v_lshl_add_u64 v[220:221], s[88:89], 0, v[136:137]
	s_mov_b32 m0, s57
	s_nop 0
	global_load_lds_dwordx4 v[220:221], off
	s_mov_b32 m0, s58
	s_nop 0
	global_load_lds_dwordx4 v[222:223], off
	s_waitcnt vmcnt(8)
	s_waitcnt lgkmcnt(0)
	s_cbranch_vccnz .Lhb_p2_2
	s_barrier
.Lhb_p2_2:
	s_setprio 1
	s_waitcnt lgkmcnt(0)
	v_mfma_i32_16x16x64_i8 v[62:65], v[146:149], v[184:187], v[62:65]
	v_mfma_i32_16x16x64_i8 v[58:61], v[160:163], v[184:187], v[58:61]
	v_mfma_i32_16x16x64_i8 v[46:49], v[146:149], v[192:195], v[46:49]
	v_mfma_i32_16x16x64_i8 v[42:45], v[160:163], v[192:195], v[42:45]
	v_mfma_i32_16x16x64_i8 v[30:33], v[146:149], v[200:203], v[30:33]
	v_mfma_i32_16x16x64_i8 v[26:29], v[160:163], v[200:203], v[26:29]
	v_mfma_i32_16x16x64_i8 v[14:17], v[146:149], v[208:211], v[14:17]
	v_mfma_i32_16x16x64_i8 v[10:13], v[160:163], v[208:211], v[10:13]
	v_mfma_i32_16x16x64_i8 v[62:65], v[150:153], v[188:191], v[62:65]
	v_mfma_i32_16x16x64_i8 v[58:61], v[164:167], v[188:191], v[58:61]
	v_mfma_i32_16x16x64_i8 v[46:49], v[150:153], v[196:199], v[46:49]
	v_mfma_i32_16x16x64_i8 v[42:45], v[164:167], v[196:199], v[42:45]
	v_mfma_i32_16x16x64_i8 v[30:33], v[150:153], v[204:207], v[30:33]
	v_mfma_i32_16x16x64_i8 v[26:29], v[164:167], v[204:207], v[26:29]
	v_mfma_i32_16x16x64_i8 v[14:17], v[150:153], v[212:215], v[14:17]
	v_mfma_i32_16x16x64_i8 v[10:13], v[164:167], v[212:215], v[10:13]
	s_setprio 0
	s_setprio 1
	v_mfma_i32_16x16x64_i8 v[54:57], v[168:171], v[184:187], v[54:57]
	v_mfma_i32_16x16x64_i8 v[50:53], v[176:179], v[184:187], v[50:53]
	v_mfma_i32_16x16x64_i8 v[38:41], v[168:171], v[192:195], v[38:41]
	v_mfma_i32_16x16x64_i8 v[34:37], v[176:179], v[192:195], v[34:37]
	v_mfma_i32_16x16x64_i8 v[22:25], v[168:171], v[200:203], v[22:25]
	v_mfma_i32_16x16x64_i8 v[18:21], v[176:179], v[200:203], v[18:21]
	v_mfma_i32_16x16x64_i8 v[6:9], v[168:171], v[208:211], v[6:9]
	v_mfma_i32_16x16x64_i8 v[2:5], v[176:179], v[208:211], v[2:5]
	v_mfma_i32_16x16x64_i8 v[54:57], v[172:175], v[188:191], v[54:57]
	v_mfma_i32_16x16x64_i8 v[50:53], v[180:183], v[188:191], v[50:53]
	v_mfma_i32_16x16x64_i8 v[38:41], v[172:175], v[196:199], v[38:41]
	v_mfma_i32_16x16x64_i8 v[34:37], v[180:183], v[196:199], v[34:37]
	v_mfma_i32_16x16x64_i8 v[22:25], v[172:175], v[204:207], v[22:25]
	v_mfma_i32_16x16x64_i8 v[18:21], v[180:183], v[204:207], v[18:21]
	v_mfma_i32_16x16x64_i8 v[6:9], v[172:175], v[212:215], v[6:9]
	v_mfma_i32_16x16x64_i8 v[2:5], v[180:183], v[212:215], v[2:5]
	s_setprio 0
	s_cbranch_vccz .Lhb_p2_3
	s_barrier
.Lhb_p2_3:
	s_add_i32 s19, 0, 0x18000
	v_add_u32_e32 v159, s19, v154
	s_add_i32 s22, 0, 0x1c000
	ds_read_b128 v[146:149], v159
	ds_read_b128 v[150:153], v159 offset:1024
	ds_read_b128 v[160:163], v159 offset:2048
	ds_read_b128 v[164:167], v159 offset:3072
	v_add_u32_e32 v159, s22, v154
	ds_read_b128 v[168:171], v159
	ds_read_b128 v[172:175], v159 offset:1024
	ds_read_b128 v[176:179], v159 offset:2048
	ds_read_b128 v[180:183], v159 offset:3072
	s_add_u32 s20, s88, 0x80000
	s_addc_u32 s21, s89, 0
	s_mov_b32 m0, s59
	v_lshl_add_u64 v[224:225], s[20:21], 0, v[136:137]
	ds_read_b128 v[184:187], v158 offset:32768
	ds_read_b128 v[188:191], v158 offset:33792
	ds_read_b128 v[192:195], v158 offset:34816
	ds_read_b128 v[196:199], v158 offset:35840
	ds_read_b128 v[200:203], v158 offset:36864
	ds_read_b128 v[204:207], v158 offset:37888
	ds_read_b128 v[208:211], v158 offset:38912
	ds_read_b128 v[212:215], v158 offset:39936
	global_load_lds_dwordx4 v[224:225], off
	v_lshl_add_u64 v[224:225], s[20:21], 0, v[132:133]
	s_mov_b32 m0, s61
	s_nop 0
	global_load_lds_dwordx4 v[224:225], off
	s_waitcnt vmcnt(8)
	s_waitcnt lgkmcnt(0)
	s_cbranch_vccnz .Lhb_p2_4
	s_barrier

.Lhb_p2_5:
	s_add_i32 s19, s19, s35
	v_lshl_add_u64 v[216:217], v[216:217], 0, s[4:5]
	s_mov_b32 m0, s19
	ds_read_b128 v[184:187], v158 offset:49152
	ds_read_b128 v[188:191], v158 offset:50176
	ds_read_b128 v[192:195], v158 offset:51200
	ds_read_b128 v[196:199], v158 offset:52224
	ds_read_b128 v[200:203], v158 offset:53248
	ds_read_b128 v[204:207], v158 offset:54272
	ds_read_b128 v[208:211], v158 offset:55296
	ds_read_b128 v[212:215], v158 offset:56320
	global_load_lds_dwordx4 v[216:217], off
	s_add_i32 m0, s19, 0x2000
	s_add_u32 s20, s86, 0x80080
	v_lshl_add_u64 v[216:217], v[218:219], 0, s[4:5]
	s_addc_u32 s21, s87, 0
	s_add_i32 s19, s22, s35
	global_load_lds_dwordx4 v[216:217], off
	v_lshl_add_u64 v[216:217], s[20:21], 0, v[134:135]
	s_mov_b32 m0, s19
	s_nop 0
	global_load_lds_dwordx4 v[216:217], off
	v_lshl_add_u64 v[216:217], s[20:21], 0, v[130:131]
	s_add_i32 m0, s19, 0x2000
	s_nop 0
	global_load_lds_dwordx4 v[216:217], off
	v_lshl_add_u64 v[216:217], v[220:221], 0, s[4:5]
	s_mov_b32 m0, s67
	s_nop 0
	global_load_lds_dwordx4 v[216:217], off
	v_lshl_add_u64 v[216:217], v[222:223], 0, s[4:5]
	s_mov_b32 m0, s68
	s_nop 0
	global_load_lds_dwordx4 v[216:217], off
	s_waitcnt vmcnt(8)
	s_waitcnt lgkmcnt(0)
	s_cbranch_vccnz .Lhb_p2_6
	s_barrier

.Lhb_p2_7:
	s_add_i32 s18, s18, 2
	s_add_u32 s84, s84, 0x100
	s_addc_u32 s85, s85, 0
	s_add_u32 s16, s16, 0x100
	s_addc_u32 s17, s17, 0
	s_cmp_gt_u32 s18, 29
	s_cbranch_scc0 .LBB0_213
	s_and_b64 vcc, exec, s[6:7]
	s_cbranch_vccz .LBB0_216
.LBB0_216:
	v_lshl_or_b32 v172, s92, 7, v155
	v_ashrrev_i32_e32 v173, 31, v172
	v_lshlrev_b64 v[146:147], 2, v[172:173]
	v_lshl_add_u64 v[152:153], s[80:81], 0, v[146:147]
	v_lshl_add_u64 v[146:147], s[36:37], 0, v[146:147]
	global_load_dwordx4 v[148:151], v[152:153], off
	global_load_dwordx4 v[160:163], v[152:153], off offset:16
	global_load_dwordx4 v[164:167], v[146:147], off
	global_load_dwordx4 v[168:171], v[146:147], off offset:16
	v_lshl_add_u32 v146, s82, 8, v1
	v_ashrrev_i32_e32 v147, 31, v146
	v_lshl_add_u64 v[152:153], v[146:147], 2, s[70:71]
	global_load_dword v174, v[152:153], off
	global_load_dword v192, v[152:153], off offset:64
	global_load_dword v193, v[152:153], off offset:128
	global_load_dword v194, v[152:153], off offset:192
	global_load_dword v195, v[152:153], off offset:512
	global_load_dword v196, v[152:153], off offset:576
	global_load_dword v197, v[152:153], off offset:640
	global_load_dword v198, v[152:153], off offset:704
	v_cvt_f32_i32_e32 v177, v127
	v_cvt_f32_i32_e32 v176, v126
	v_cvt_f32_i32_e32 v185, v119
	v_cvt_f32_i32_e32 v184, v118
	v_cvt_f32_i32_e32 v179, v129
	v_cvt_f32_i32_e32 v178, v128
	v_cvt_f32_i32_e32 v187, v121
	v_cvt_f32_i32_e32 v186, v120
	v_cvt_f32_i32_e32 v189, v115
	v_cvt_f32_i32_e32 v188, v114
	v_mov_b64_e32 v[114:115], s[38:39]
	v_cvt_f32_i32_e32 v191, v117
	v_cvt_f32_i32_e32 v190, v116
	v_mad_i64_i32 v[118:119], s[8:9], v146, s91, v[114:115]
	v_lshlrev_b64 v[116:117], 1, v[172:173]
	v_cvt_f32_i32_e32 v181, v123
	v_cvt_f32_i32_e32 v180, v122
	v_lshl_add_u64 v[172:173], v[118:119], 0, v[116:117]
	v_cvt_f32_i32_e32 v183, v125
	v_cvt_f32_i32_e32 v182, v124
	v_cvt_f32_i32_e32 v111, v111
	v_cvt_f32_i32_e32 v110, v110
	v_cvt_f32_i32_e32 v103, v103
	v_cvt_f32_i32_e32 v102, v102
	v_cvt_f32_i32_e32 v113, v113
	v_cvt_f32_i32_e32 v112, v112
	v_cvt_f32_i32_e32 v107, v107
	v_cvt_f32_i32_e32 v106, v106
	v_cvt_f32_i32_e32 v99, v99
	v_cvt_f32_i32_e32 v98, v98
	v_cvt_f32_i32_e32 v101, v101
	v_cvt_f32_i32_e32 v100, v100
	v_cvt_f32_i32_e32 v109, v109
	v_cvt_f32_i32_e32 v108, v108
	v_cvt_f32_i32_e32 v105, v105
	v_cvt_f32_i32_e32 v104, v104
	v_cvt_f32_i32_e32 v95, v95
	v_cvt_f32_i32_e32 v94, v94
	v_cvt_f32_i32_e32 v87, v87
	v_cvt_f32_i32_e32 v86, v86
	v_cvt_f32_i32_e32 v97, v97
	v_cvt_f32_i32_e32 v96, v96
	v_cvt_f32_i32_e32 v91, v91
	v_cvt_f32_i32_e32 v90, v90
	v_cvt_f32_i32_e32 v83, v83
	v_cvt_f32_i32_e32 v82, v82
	v_cvt_f32_i32_e32 v85, v85
	v_cvt_f32_i32_e32 v84, v84
	v_cvt_f32_i32_e32 v93, v93
	v_cvt_f32_i32_e32 v92, v92
	v_cvt_f32_i32_e32 v89, v89
	v_cvt_f32_i32_e32 v88, v88
	v_cvt_f32_i32_e32 v79, v79
	v_cvt_f32_i32_e32 v78, v78
	v_cvt_f32_i32_e32 v81, v81
	v_cvt_f32_i32_e32 v80, v80
	v_cvt_f32_i32_e32 v71, v71
	v_cvt_f32_i32_e32 v70, v70
	v_cvt_f32_i32_e32 v75, v75
	v_cvt_f32_i32_e32 v74, v74
	v_cvt_f32_i32_e32 v67, v67
	v_cvt_f32_i32_e32 v66, v66
	v_cvt_f32_i32_e32 v69, v69
	v_cvt_f32_i32_e32 v68, v68
	v_cvt_f32_i32_e32 v77, v77
	v_cvt_f32_i32_e32 v76, v76
	v_cvt_f32_i32_e32 v73, v73
	v_cvt_f32_i32_e32 v72, v72
	v_cvt_f32_i32_e32 v63, v63
	v_cvt_f32_i32_e32 v62, v62
	v_cvt_f32_i32_e32 v65, v65
	v_cvt_f32_i32_e32 v64, v64
	s_waitcnt vmcnt(0)
	v_pk_mul_f32 v[120:121], v[148:149], s[40:41] op_sel_hi:[1,0]
	v_pk_mul_f32 v[128:129], v[164:165], s[40:41] op_sel_hi:[1,0]
	v_pk_mul_f32 v[118:119], v[150:151], s[40:41] op_sel_hi:[1,0]
	v_pk_mul_f32 v[122:123], v[162:163], s[40:41] op_sel_hi:[1,0]
	v_pk_mul_f32 v[126:127], v[166:167], s[40:41] op_sel_hi:[1,0]
	v_pk_mul_f32 v[148:149], v[170:171], s[40:41] op_sel_hi:[1,0]
	v_pk_mul_f32 v[162:163], v[120:121], v[176:177]
	v_pk_mul_f32 v[170:171], v[128:129], v[184:185]
	v_pk_mul_f32 v[124:125], v[160:161], s[40:41] op_sel_hi:[1,0]
	v_pk_mul_f32 v[150:151], v[168:169], s[40:41] op_sel_hi:[1,0]
	v_pk_mul_f32 v[160:161], v[118:119], v[178:179]
	v_pk_mul_f32 v[168:169], v[126:127], v[186:187]
	v_pk_mul_f32 v[162:163], v[162:163], v[174:175] op_sel_hi:[1,0]
	v_pk_mul_f32 v[170:171], v[170:171], v[174:175] op_sel_hi:[1,0]
	v_pk_mul_f32 v[160:161], v[160:161], v[174:175] op_sel_hi:[1,0]
	v_pk_mul_f32 v[168:169], v[168:169], v[174:175] op_sel_hi:[1,0]
	v_mul_f32_e32 v147, v162, v170
	v_mul_f32_e32 v159, 0xbfb8aa3b, v162
	v_mul_f32_e32 v162, v163, v171
	v_mul_f32_e32 v163, 0xbfb8aa3b, v163
	v_mul_f32_e32 v168, v160, v168
	v_mul_f32_e32 v160, 0xbfb8aa3b, v160
	v_exp_f32_e32 v159, v159
	v_exp_f32_e32 v163, v163
	v_exp_f32_e32 v160, v160
	v_pk_mul_f32 v[164:165], v[122:123], v[182:183]
	v_pk_mul_f32 v[166:167], v[124:125], v[180:181]
	v_pk_mul_f32 v[176:177], v[148:149], v[190:191]
	v_pk_mul_f32 v[178:179], v[150:151], v[188:189]
	v_add_f32_e32 v159, 1.0, v159
	v_add_f32_e32 v163, 1.0, v163
	v_pk_mul_f32 v[164:165], v[164:165], v[174:175] op_sel_hi:[1,0]
	v_pk_mul_f32 v[166:167], v[166:167], v[174:175] op_sel_hi:[1,0]
	v_pk_mul_f32 v[176:177], v[176:177], v[174:175] op_sel_hi:[1,0]
	v_pk_mul_f32 v[174:175], v[178:179], v[174:175] op_sel_hi:[1,0]
	v_add_f32_e32 v160, 1.0, v160
	v_rcp_f32_e32 v159, v159
	v_rcp_f32_e32 v163, v163
	v_mul_f32_e32 v169, v161, v169
	v_mul_f32_e32 v161, 0xbfb8aa3b, v161
	v_mul_f32_e32 v170, v166, v174
	v_mul_f32_e32 v166, 0xbfb8aa3b, v166
	v_mul_f32_e32 v171, v167, v175
	v_mul_f32_e32 v167, 0xbfb8aa3b, v167
	v_rcp_f32_e32 v160, v160
	v_exp_f32_e32 v161, v161
	v_exp_f32_e32 v166, v166
	v_exp_f32_e32 v167, v167
	v_mul_f32_e32 v174, 0xbfb8aa3b, v164
	v_mul_f32_e32 v175, 0xbfb8aa3b, v165
	v_exp_f32_e32 v174, v174
	v_mul_f32_e32 v147, v147, v159
	v_mul_f32_e32 v159, v162, v163
	v_mul_f32_e32 v162, v168, v160
	v_cvt_pkrtz_f16_f32 v160, v147, v159
	v_exp_f32_e32 v147, v175
	v_add_f32_e32 v161, 1.0, v161
	v_add_f32_e32 v166, 1.0, v166
	v_add_f32_e32 v167, 1.0, v167
	v_rcp_f32_e32 v161, v161
	v_rcp_f32_e32 v166, v166
	v_rcp_f32_e32 v167, v167
	v_add_f32_e32 v159, 1.0, v174
	v_rcp_f32_e32 v159, v159
	v_add_f32_e32 v147, 1.0, v147
	v_rcp_f32_e32 v147, v147
	v_mul_f32_e32 v161, v169, v161
	v_mul_f32_e32 v163, v170, v166
	v_mul_f32_e32 v166, v171, v167
	v_cvt_pkrtz_f16_f32 v161, v162, v161
	v_cvt_pkrtz_f16_f32 v162, v163, v166
	v_mul_f32_e32 v163, v164, v176
	v_mul_f32_e32 v159, v163, v159
	v_mul_f32_e32 v163, v165, v177
	v_mul_f32_e32 v147, v163, v147
	v_cvt_pkrtz_f16_f32 v163, v159, v147
	global_store_dwordx4 v[172:173], v[160:163], off
	v_pk_mul_f32 v[110:111], v[120:121], v[110:111]
	v_pk_mul_f32 v[102:103], v[128:129], v[102:103]
	v_or_b32_e32 v160, 16, v146
	v_ashrrev_i32_e32 v161, 31, v160
	v_lshl_add_u64 v[162:163], v[160:161], 2, s[70:71]
	v_mov_b32_e32 v162, v192
	v_pk_mul_f32 v[112:113], v[118:119], v[112:113]
	v_pk_mul_f32 v[106:107], v[124:125], v[106:107]
	v_pk_mul_f32 v[100:101], v[148:149], v[100:101]
	v_pk_mul_f32 v[98:99], v[150:151], v[98:99]
	v_pk_mul_f32 v[108:109], v[122:123], v[108:109]
	v_pk_mul_f32 v[104:105], v[126:127], v[104:105]
	v_mad_i64_i32 v[160:161], s[8:9], v160, s91, v[114:115]
	v_lshl_add_u64 v[160:161], v[160:161], 0, v[116:117]
	v_pk_mul_f32 v[94:95], v[120:121], v[94:95]
	v_pk_mul_f32 v[86:87], v[128:129], v[86:87]
	v_pk_mul_f32 v[96:97], v[118:119], v[96:97]
	v_pk_mul_f32 v[90:91], v[124:125], v[90:91]
	v_pk_mul_f32 v[84:85], v[148:149], v[84:85]
	v_pk_mul_f32 v[82:83], v[150:151], v[82:83]
	v_pk_mul_f32 v[92:93], v[122:123], v[92:93]
	v_pk_mul_f32 v[88:89], v[126:127], v[88:89]
	v_pk_mul_f32 v[80:81], v[118:119], v[80:81]
	v_pk_mul_f32 v[78:79], v[120:121], v[78:79]
	v_pk_mul_f32 v[70:71], v[128:129], v[70:71]
	v_pk_mul_f32 v[74:75], v[124:125], v[74:75]
	v_pk_mul_f32 v[68:69], v[148:149], v[68:69]
	v_pk_mul_f32 v[66:67], v[150:151], v[66:67]
	v_pk_mul_f32 v[76:77], v[122:123], v[76:77]
	v_pk_mul_f32 v[72:73], v[126:127], v[72:73]
	v_cvt_f32_i32_e32 v59, v59
	v_cvt_f32_i32_e32 v58, v58
	v_cvt_f32_i32_e32 v61, v61
	v_cvt_f32_i32_e32 v60, v60
	v_cvt_f32_i32_e32 v55, v55
	v_cvt_f32_i32_e32 v54, v54
	v_cvt_f32_i32_e32 v57, v57
	v_cvt_f32_i32_e32 v56, v56
	v_cvt_f32_i32_e32 v51, v51
	v_cvt_f32_i32_e32 v50, v50
	v_cvt_f32_i32_e32 v53, v53
	v_cvt_f32_i32_e32 v52, v52
	v_pk_mul_f32 v[64:65], v[118:119], v[64:65]
	v_pk_mul_f32 v[62:63], v[120:121], v[62:63]
	v_pk_mul_f32 v[60:61], v[122:123], v[60:61]
	v_pk_mul_f32 v[58:59], v[124:125], v[58:59]
	v_pk_mul_f32 v[56:57], v[126:127], v[56:57]
	v_pk_mul_f32 v[54:55], v[128:129], v[54:55]
	v_pk_mul_f32 v[52:53], v[148:149], v[52:53]
	v_pk_mul_f32 v[50:51], v[150:151], v[50:51]
	v_cvt_f32_i32_e32 v47, v47
	v_cvt_f32_i32_e32 v46, v46
	v_cvt_f32_i32_e32 v49, v49
	v_cvt_f32_i32_e32 v48, v48
	v_cvt_f32_i32_e32 v43, v43
	v_cvt_f32_i32_e32 v42, v42
	v_cvt_f32_i32_e32 v45, v45
	v_cvt_f32_i32_e32 v44, v44
	v_cvt_f32_i32_e32 v39, v39
	v_cvt_f32_i32_e32 v38, v38
	v_cvt_f32_i32_e32 v41, v41
	v_cvt_f32_i32_e32 v40, v40
	v_cvt_f32_i32_e32 v35, v35
	v_cvt_f32_i32_e32 v34, v34
	v_cvt_f32_i32_e32 v37, v37
	v_cvt_f32_i32_e32 v36, v36
	v_pk_mul_f32 v[48:49], v[118:119], v[48:49]
	v_pk_mul_f32 v[46:47], v[120:121], v[46:47]
	v_pk_mul_f32 v[44:45], v[122:123], v[44:45]
	v_pk_mul_f32 v[42:43], v[124:125], v[42:43]
	v_pk_mul_f32 v[40:41], v[126:127], v[40:41]
	v_pk_mul_f32 v[38:39], v[128:129], v[38:39]
	v_pk_mul_f32 v[36:37], v[148:149], v[36:37]
	v_pk_mul_f32 v[34:35], v[150:151], v[34:35]
	v_cvt_f32_i32_e32 v31, v31
	v_cvt_f32_i32_e32 v30, v30
	v_cvt_f32_i32_e32 v33, v33
	v_cvt_f32_i32_e32 v32, v32
	v_cvt_f32_i32_e32 v27, v27
	v_cvt_f32_i32_e32 v26, v26
	v_cvt_f32_i32_e32 v29, v29
	v_cvt_f32_i32_e32 v28, v28
	v_cvt_f32_i32_e32 v23, v23
	v_cvt_f32_i32_e32 v22, v22
	v_pk_mul_f32 v[110:111], v[110:111], v[162:163] op_sel_hi:[1,0]
	v_pk_mul_f32 v[102:103], v[102:103], v[162:163] op_sel_hi:[1,0]
	v_pk_mul_f32 v[112:113], v[112:113], v[162:163] op_sel_hi:[1,0]
	v_pk_mul_f32 v[106:107], v[106:107], v[162:163] op_sel_hi:[1,0]
	v_pk_mul_f32 v[164:165], v[100:101], v[162:163] op_sel_hi:[1,0]
	v_pk_mul_f32 v[98:99], v[98:99], v[162:163] op_sel_hi:[1,0]
	v_mul_f32_e32 v100, v110, v102
	v_mul_f32_e32 v101, 0xbfb8aa3b, v110
	v_mul_f32_e32 v102, v111, v103
	v_mul_f32_e32 v103, 0xbfb8aa3b, v111
	v_mul_f32_e32 v110, 0xbfb8aa3b, v112
	v_mul_f32_e32 v111, 0xbfb8aa3b, v113
	v_mul_f32_e32 v98, v106, v98
	v_mul_f32_e32 v106, 0xbfb8aa3b, v106
	v_exp_f32_e32 v101, v101
	v_exp_f32_e32 v103, v103
	v_mul_f32_e32 v99, v107, v99
	v_mul_f32_e32 v107, 0xbfb8aa3b, v107
	v_exp_f32_e32 v110, v110
	v_exp_f32_e32 v111, v111
	v_exp_f32_e32 v106, v106
	v_exp_f32_e32 v107, v107
	v_pk_mul_f32 v[108:109], v[108:109], v[162:163] op_sel_hi:[1,0]
	v_pk_mul_f32 v[104:105], v[104:105], v[162:163] op_sel_hi:[1,0]
	v_add_f32_e32 v101, 1.0, v101
	v_add_f32_e32 v103, 1.0, v103
	v_mul_f32_e32 v104, v112, v104
	v_mul_f32_e32 v112, 0xbfb8aa3b, v108
	v_add_f32_e32 v110, 1.0, v110
	v_add_f32_e32 v111, 1.0, v111
	v_add_f32_e32 v106, 1.0, v106
	v_rcp_f32_e32 v101, v101
	v_rcp_f32_e32 v103, v103
	v_mul_f32_e32 v105, v113, v105
	v_mul_f32_e32 v113, 0xbfb8aa3b, v109
	v_exp_f32_e32 v112, v112
	v_add_f32_e32 v107, 1.0, v107
	v_rcp_f32_e32 v110, v110
	v_rcp_f32_e32 v111, v111
	v_rcp_f32_e32 v106, v106
	v_exp_f32_e32 v113, v113
	v_rcp_f32_e32 v107, v107
	v_mul_f32_e32 v100, v100, v101
	v_mul_f32_e32 v101, v102, v103
	v_mul_f32_e32 v102, v104, v110
	v_mul_f32_e32 v103, v105, v111
	v_mul_f32_e32 v104, v98, v106
	v_cvt_pkrtz_f16_f32 v98, v100, v101
	v_add_f32_e32 v101, 1.0, v112
	v_mul_f32_e32 v105, v99, v107
	v_cvt_pkrtz_f16_f32 v99, v102, v103
	v_rcp_f32_e32 v101, v101
	v_add_f32_e32 v102, 1.0, v113
	v_rcp_f32_e32 v102, v102
	v_mul_f32_e32 v103, v108, v164
	v_mul_f32_e32 v101, v103, v101
	v_mul_f32_e32 v103, v109, v165
	v_mul_f32_e32 v102, v103, v102
	v_cvt_pkrtz_f16_f32 v100, v104, v105
	v_cvt_pkrtz_f16_f32 v101, v101, v102
	global_store_dwordx4 v[160:161], v[98:101], off
	v_cvt_f32_i32_e32 v25, v25
	v_cvt_f32_i32_e32 v24, v24
	v_or_b32_e32 v98, 32, v146
	v_ashrrev_i32_e32 v99, 31, v98
	v_lshl_add_u64 v[100:101], v[98:99], 2, s[70:71]
	v_mov_b32_e32 v100, v193
	v_mad_i64_i32 v[98:99], s[8:9], v98, s91, v[114:115]
	v_lshl_add_u64 v[98:99], v[98:99], 0, v[116:117]
	v_cvt_f32_i32_e32 v19, v19
	v_cvt_f32_i32_e32 v18, v18
	v_cvt_f32_i32_e32 v21, v21
	v_cvt_f32_i32_e32 v20, v20
	v_pk_mul_f32 v[32:33], v[118:119], v[32:33]
	v_pk_mul_f32 v[30:31], v[120:121], v[30:31]
	v_pk_mul_f32 v[28:29], v[122:123], v[28:29]
	v_pk_mul_f32 v[26:27], v[124:125], v[26:27]
	v_pk_mul_f32 v[24:25], v[126:127], v[24:25]
	v_pk_mul_f32 v[22:23], v[128:129], v[22:23]
	v_pk_mul_f32 v[20:21], v[148:149], v[20:21]
	v_pk_mul_f32 v[18:19], v[150:151], v[18:19]
	v_cvt_f32_i32_e32 v15, v15
	v_cvt_f32_i32_e32 v14, v14
	v_cvt_f32_i32_e32 v17, v17
	v_cvt_f32_i32_e32 v16, v16
	v_cvt_f32_i32_e32 v11, v11
	v_cvt_f32_i32_e32 v10, v10
	v_cvt_f32_i32_e32 v13, v13
	v_cvt_f32_i32_e32 v12, v12
	v_cvt_f32_i32_e32 v7, v7
	v_cvt_f32_i32_e32 v6, v6
	v_cvt_f32_i32_e32 v9, v9
	v_cvt_f32_i32_e32 v8, v8
	v_cvt_f32_i32_e32 v3, v3
	v_cvt_f32_i32_e32 v2, v2
	v_cvt_f32_i32_e32 v5, v5
	v_cvt_f32_i32_e32 v4, v4
	v_pk_mul_f32 v[16:17], v[118:119], v[16:17]
	v_pk_mul_f32 v[14:15], v[120:121], v[14:15]
	v_pk_mul_f32 v[12:13], v[122:123], v[12:13]
	v_pk_mul_f32 v[10:11], v[124:125], v[10:11]
	v_pk_mul_f32 v[8:9], v[126:127], v[8:9]
	v_pk_mul_f32 v[6:7], v[128:129], v[6:7]
	v_pk_mul_f32 v[4:5], v[148:149], v[4:5]
	v_pk_mul_f32 v[2:3], v[150:151], v[2:3]
	s_andn2_b64 vcc, exec, s[2:3]
	s_mov_b64 s[2:3], -1
	v_pk_mul_f32 v[94:95], v[94:95], v[100:101] op_sel_hi:[1,0]
	v_pk_mul_f32 v[86:87], v[86:87], v[100:101] op_sel_hi:[1,0]
	v_pk_mul_f32 v[96:97], v[96:97], v[100:101] op_sel_hi:[1,0]
	v_pk_mul_f32 v[90:91], v[90:91], v[100:101] op_sel_hi:[1,0]
	v_pk_mul_f32 v[102:103], v[84:85], v[100:101] op_sel_hi:[1,0]
	v_pk_mul_f32 v[82:83], v[82:83], v[100:101] op_sel_hi:[1,0]
	v_mul_f32_e32 v84, v94, v86
	v_mul_f32_e32 v85, 0xbfb8aa3b, v94
	v_mul_f32_e32 v86, v95, v87
	v_mul_f32_e32 v87, 0xbfb8aa3b, v95
	v_mul_f32_e32 v94, 0xbfb8aa3b, v96
	v_mul_f32_e32 v82, v90, v82
	v_mul_f32_e32 v90, 0xbfb8aa3b, v90
	v_exp_f32_e32 v85, v85
	v_exp_f32_e32 v87, v87
	v_exp_f32_e32 v94, v94
	v_exp_f32_e32 v90, v90
	v_mul_f32_e32 v95, 0xbfb8aa3b, v97
	v_pk_mul_f32 v[92:93], v[92:93], v[100:101] op_sel_hi:[1,0]
	v_pk_mul_f32 v[88:89], v[88:89], v[100:101] op_sel_hi:[1,0]
	v_mul_f32_e32 v83, v91, v83
	v_mul_f32_e32 v91, 0xbfb8aa3b, v91
	v_exp_f32_e32 v95, v95
	v_add_f32_e32 v85, 1.0, v85
	v_add_f32_e32 v87, 1.0, v87
	v_mul_f32_e32 v88, v96, v88
	v_mul_f32_e32 v89, v97, v89
	v_mul_f32_e32 v96, 0xbfb8aa3b, v92
	v_mul_f32_e32 v97, 0xbfb8aa3b, v93
	v_exp_f32_e32 v91, v91
	v_add_f32_e32 v94, 1.0, v94
	v_add_f32_e32 v90, 1.0, v90
	v_rcp_f32_e32 v85, v85
	v_rcp_f32_e32 v87, v87
	v_exp_f32_e32 v96, v96
	v_exp_f32_e32 v97, v97
	v_rcp_f32_e32 v94, v94
	v_rcp_f32_e32 v90, v90
	v_add_f32_e32 v95, 1.0, v95
	v_add_f32_e32 v91, 1.0, v91
	v_rcp_f32_e32 v95, v95
	v_mul_f32_e32 v84, v84, v85
	v_mul_f32_e32 v85, v86, v87
	v_add_f32_e32 v96, 1.0, v96
	v_rcp_f32_e32 v91, v91
	v_mul_f32_e32 v86, v88, v94
	v_mul_f32_e32 v88, v82, v90
	v_cvt_pkrtz_f16_f32 v82, v84, v85
	v_add_f32_e32 v85, 1.0, v97
	v_rcp_f32_e32 v96, v96
	v_rcp_f32_e32 v85, v85
	v_mul_f32_e32 v87, v89, v95
	v_mul_f32_e32 v89, v83, v91
	v_cvt_pkrtz_f16_f32 v83, v86, v87
	v_mul_f32_e32 v86, v92, v102
	v_mul_f32_e32 v87, v93, v103
	v_mul_f32_e32 v86, v86, v96
	v_mul_f32_e32 v85, v87, v85
	v_cvt_pkrtz_f16_f32 v84, v88, v89
	v_cvt_pkrtz_f16_f32 v85, v86, v85
	global_store_dwordx4 v[98:99], v[82:85], off
	s_nop 1
	v_or_b32_e32 v82, 48, v146
	v_ashrrev_i32_e32 v83, 31, v82
	v_lshl_add_u64 v[84:85], v[82:83], 2, s[70:71]
	v_mov_b32_e32 v84, v194
	v_mad_i64_i32 v[82:83], s[8:9], v82, s91, v[114:115]
	v_lshl_add_u64 v[82:83], v[82:83], 0, v[116:117]
	v_pk_mul_f32 v[80:81], v[80:81], v[84:85] op_sel_hi:[1,0]
	v_pk_mul_f32 v[78:79], v[78:79], v[84:85] op_sel_hi:[1,0]
	v_pk_mul_f32 v[70:71], v[70:71], v[84:85] op_sel_hi:[1,0]
	v_pk_mul_f32 v[74:75], v[74:75], v[84:85] op_sel_hi:[1,0]
	v_pk_mul_f32 v[86:87], v[68:69], v[84:85] op_sel_hi:[1,0]
	v_pk_mul_f32 v[66:67], v[66:67], v[84:85] op_sel_hi:[1,0]
	v_mul_f32_e32 v68, v78, v70
	v_mul_f32_e32 v69, 0xbfb8aa3b, v78
	v_mul_f32_e32 v70, v79, v71
	v_mul_f32_e32 v71, 0xbfb8aa3b, v79
	v_mul_f32_e32 v78, 0xbfb8aa3b, v80
	v_mul_f32_e32 v79, 0xbfb8aa3b, v81
	v_pk_mul_f32 v[76:77], v[76:77], v[84:85] op_sel_hi:[1,0]
	v_pk_mul_f32 v[72:73], v[72:73], v[84:85] op_sel_hi:[1,0]
	v_mul_f32_e32 v66, v74, v66
	v_mul_f32_e32 v74, 0xbfb8aa3b, v74
	v_mul_f32_e32 v67, v75, v67
	v_mul_f32_e32 v75, 0xbfb8aa3b, v75
	v_exp_f32_e32 v69, v69
	v_exp_f32_e32 v71, v71
	v_exp_f32_e32 v78, v78
	v_exp_f32_e32 v79, v79
	v_mul_f32_e32 v72, v80, v72
	v_mul_f32_e32 v73, v81, v73
	v_mul_f32_e32 v80, 0xbfb8aa3b, v76
	v_mul_f32_e32 v81, 0xbfb8aa3b, v77
	v_exp_f32_e32 v74, v74
	v_exp_f32_e32 v75, v75
	v_exp_f32_e32 v80, v80
	v_exp_f32_e32 v81, v81
	v_add_f32_e32 v69, 1.0, v69
	v_add_f32_e32 v71, 1.0, v71
	v_add_f32_e32 v78, 1.0, v78
	v_add_f32_e32 v79, 1.0, v79
	v_add_f32_e32 v74, 1.0, v74
	v_add_f32_e32 v75, 1.0, v75
	v_rcp_f32_e32 v69, v69
	v_rcp_f32_e32 v71, v71
	v_rcp_f32_e32 v78, v78
	v_rcp_f32_e32 v79, v79
	v_add_f32_e32 v80, 1.0, v80
	v_add_f32_e32 v81, 1.0, v81
	v_rcp_f32_e32 v74, v74
	v_rcp_f32_e32 v75, v75
	v_rcp_f32_e32 v80, v80
	v_rcp_f32_e32 v81, v81
	v_mul_f32_e32 v68, v68, v69
	v_mul_f32_e32 v69, v70, v71
	v_mul_f32_e32 v70, v72, v78
	v_mul_f32_e32 v71, v73, v79
	v_mul_f32_e32 v72, v66, v74
	v_mul_f32_e32 v73, v67, v75
	v_cvt_pkrtz_f16_f32 v66, v68, v69
	v_cvt_pkrtz_f16_f32 v67, v70, v71
	v_mul_f32_e32 v69, v76, v86
	v_mul_f32_e32 v70, v77, v87
	v_mul_f32_e32 v69, v69, v80
	v_mul_f32_e32 v70, v70, v81
	v_cvt_pkrtz_f16_f32 v68, v72, v73
	v_cvt_pkrtz_f16_f32 v69, v69, v70
	global_store_dwordx4 v[82:83], v[66:69], off
	s_nop 1
	v_mov_b32_e32 v66, v195
	v_add_u32_e32 v67, 0x80, v146
	v_mad_i64_i32 v[68:69], s[8:9], v67, s91, v[114:115]
	v_lshl_add_u64 v[68:69], v[68:69], 0, v[116:117]
	v_pk_mul_f32 v[64:65], v[64:65], v[66:67] op_sel_hi:[1,0]
	v_pk_mul_f32 v[62:63], v[62:63], v[66:67] op_sel_hi:[1,0]
	v_pk_mul_f32 v[60:61], v[60:61], v[66:67] op_sel_hi:[1,0]
	v_pk_mul_f32 v[58:59], v[58:59], v[66:67] op_sel_hi:[1,0]
	v_pk_mul_f32 v[56:57], v[56:57], v[66:67] op_sel_hi:[1,0]
	v_pk_mul_f32 v[54:55], v[54:55], v[66:67] op_sel_hi:[1,0]
	v_pk_mul_f32 v[52:53], v[52:53], v[66:67] op_sel_hi:[1,0]
	v_pk_mul_f32 v[50:51], v[50:51], v[66:67] op_sel_hi:[1,0]
	v_mul_f32_e32 v54, v62, v54
	v_mul_f32_e32 v62, 0xbfb8aa3b, v62
	v_mul_f32_e32 v55, v63, v55
	v_mul_f32_e32 v63, 0xbfb8aa3b, v63
	v_mul_f32_e32 v56, v64, v56
	v_mul_f32_e32 v64, 0xbfb8aa3b, v64
	v_mul_f32_e32 v57, v65, v57
	v_mul_f32_e32 v65, 0xbfb8aa3b, v65
	v_mul_f32_e32 v50, v58, v50
	v_mul_f32_e32 v58, 0xbfb8aa3b, v58
	v_mul_f32_e32 v51, v59, v51
	v_mul_f32_e32 v59, 0xbfb8aa3b, v59
	v_mul_f32_e32 v52, v60, v52
	v_mul_f32_e32 v60, 0xbfb8aa3b, v60
	v_mul_f32_e32 v53, v61, v53
	v_mul_f32_e32 v61, 0xbfb8aa3b, v61
	v_exp_f32_e32 v62, v62
	v_exp_f32_e32 v63, v63
	v_exp_f32_e32 v64, v64
	v_exp_f32_e32 v65, v65
	v_exp_f32_e32 v58, v58
	v_exp_f32_e32 v59, v59
	v_exp_f32_e32 v60, v60
	v_exp_f32_e32 v61, v61
	v_add_f32_e32 v62, 1.0, v62
	v_add_f32_e32 v63, 1.0, v63
	v_add_f32_e32 v64, 1.0, v64
	v_add_f32_e32 v65, 1.0, v65
	v_add_f32_e32 v58, 1.0, v58
	v_add_f32_e32 v59, 1.0, v59
	v_add_f32_e32 v60, 1.0, v60
	v_add_f32_e32 v61, 1.0, v61
	v_rcp_f32_e32 v62, v62
	v_rcp_f32_e32 v63, v63
	v_rcp_f32_e32 v64, v64
	v_rcp_f32_e32 v65, v65
	v_rcp_f32_e32 v58, v58
	v_rcp_f32_e32 v59, v59
	v_rcp_f32_e32 v60, v60
	v_rcp_f32_e32 v61, v61
	v_mul_f32_e32 v54, v54, v62
	v_mul_f32_e32 v55, v55, v63
	v_mul_f32_e32 v56, v56, v64
	v_mul_f32_e32 v57, v57, v65
	v_mul_f32_e32 v58, v50, v58
	v_mul_f32_e32 v59, v51, v59
	v_mul_f32_e32 v60, v52, v60
	v_mul_f32_e32 v53, v53, v61
	v_cvt_pkrtz_f16_f32 v50, v54, v55
	v_cvt_pkrtz_f16_f32 v51, v56, v57
	v_cvt_pkrtz_f16_f32 v52, v58, v59
	v_cvt_pkrtz_f16_f32 v53, v60, v53
	global_store_dwordx4 v[68:69], v[50:53], off
	s_nop 1
	v_mov_b32_e32 v50, v196
	v_add_u32_e32 v51, 0x90, v146
	v_mad_i64_i32 v[52:53], s[8:9], v51, s91, v[114:115]
	v_lshl_add_u64 v[52:53], v[52:53], 0, v[116:117]
	v_pk_mul_f32 v[48:49], v[48:49], v[50:51] op_sel_hi:[1,0]
	v_pk_mul_f32 v[46:47], v[46:47], v[50:51] op_sel_hi:[1,0]
	v_pk_mul_f32 v[44:45], v[44:45], v[50:51] op_sel_hi:[1,0]
	v_pk_mul_f32 v[42:43], v[42:43], v[50:51] op_sel_hi:[1,0]
	v_pk_mul_f32 v[40:41], v[40:41], v[50:51] op_sel_hi:[1,0]
	v_pk_mul_f32 v[38:39], v[38:39], v[50:51] op_sel_hi:[1,0]
	v_pk_mul_f32 v[36:37], v[36:37], v[50:51] op_sel_hi:[1,0]
	v_pk_mul_f32 v[34:35], v[34:35], v[50:51] op_sel_hi:[1,0]
	v_mul_f32_e32 v38, v46, v38
	v_mul_f32_e32 v46, 0xbfb8aa3b, v46
	v_mul_f32_e32 v39, v47, v39
	v_mul_f32_e32 v47, 0xbfb8aa3b, v47
	v_mul_f32_e32 v40, v48, v40
	v_mul_f32_e32 v48, 0xbfb8aa3b, v48
	v_mul_f32_e32 v41, v49, v41
	v_mul_f32_e32 v49, 0xbfb8aa3b, v49
	v_mul_f32_e32 v34, v42, v34
	v_mul_f32_e32 v42, 0xbfb8aa3b, v42
	v_mul_f32_e32 v35, v43, v35
	v_mul_f32_e32 v43, 0xbfb8aa3b, v43
	v_mul_f32_e32 v36, v44, v36
	v_mul_f32_e32 v44, 0xbfb8aa3b, v44
	v_mul_f32_e32 v37, v45, v37
	v_mul_f32_e32 v45, 0xbfb8aa3b, v45
	v_exp_f32_e32 v46, v46
	v_exp_f32_e32 v47, v47
	v_exp_f32_e32 v48, v48
	v_exp_f32_e32 v49, v49
	v_exp_f32_e32 v42, v42
	v_exp_f32_e32 v43, v43
	v_exp_f32_e32 v44, v44
	v_exp_f32_e32 v45, v45
	v_add_f32_e32 v46, 1.0, v46
	v_add_f32_e32 v47, 1.0, v47
	v_add_f32_e32 v48, 1.0, v48
	v_add_f32_e32 v49, 1.0, v49
	v_add_f32_e32 v42, 1.0, v42
	v_add_f32_e32 v43, 1.0, v43
	v_add_f32_e32 v44, 1.0, v44
	v_add_f32_e32 v45, 1.0, v45
	v_rcp_f32_e32 v46, v46
	v_rcp_f32_e32 v47, v47
	v_rcp_f32_e32 v48, v48
	v_rcp_f32_e32 v49, v49
	v_rcp_f32_e32 v42, v42
	v_rcp_f32_e32 v43, v43
	v_rcp_f32_e32 v44, v44
	v_rcp_f32_e32 v45, v45
	v_mul_f32_e32 v38, v38, v46
	v_mul_f32_e32 v39, v39, v47
	v_mul_f32_e32 v40, v40, v48
	v_mul_f32_e32 v41, v41, v49
	v_mul_f32_e32 v42, v34, v42
	v_mul_f32_e32 v43, v35, v43
	v_mul_f32_e32 v44, v36, v44
	v_mul_f32_e32 v37, v37, v45
	v_cvt_pkrtz_f16_f32 v34, v38, v39
	v_cvt_pkrtz_f16_f32 v35, v40, v41
	v_cvt_pkrtz_f16_f32 v36, v42, v43
	v_cvt_pkrtz_f16_f32 v37, v44, v37
	global_store_dwordx4 v[52:53], v[34:37], off
	s_nop 1
	v_mov_b32_e32 v34, v197
	v_add_u32_e32 v35, 0xa0, v146
	v_mad_i64_i32 v[36:37], s[8:9], v35, s91, v[114:115]
	v_lshl_add_u64 v[36:37], v[36:37], 0, v[116:117]
	v_pk_mul_f32 v[32:33], v[32:33], v[34:35] op_sel_hi:[1,0]
	v_pk_mul_f32 v[30:31], v[30:31], v[34:35] op_sel_hi:[1,0]
	v_pk_mul_f32 v[28:29], v[28:29], v[34:35] op_sel_hi:[1,0]
	v_pk_mul_f32 v[26:27], v[26:27], v[34:35] op_sel_hi:[1,0]
	v_pk_mul_f32 v[24:25], v[24:25], v[34:35] op_sel_hi:[1,0]
	v_pk_mul_f32 v[22:23], v[22:23], v[34:35] op_sel_hi:[1,0]
	v_pk_mul_f32 v[20:21], v[20:21], v[34:35] op_sel_hi:[1,0]
	v_pk_mul_f32 v[18:19], v[18:19], v[34:35] op_sel_hi:[1,0]
	v_mul_f32_e32 v22, v30, v22
	v_mul_f32_e32 v30, 0xbfb8aa3b, v30
	v_mul_f32_e32 v23, v31, v23
	v_mul_f32_e32 v31, 0xbfb8aa3b, v31
	v_mul_f32_e32 v24, v32, v24
	v_mul_f32_e32 v32, 0xbfb8aa3b, v32
	v_mul_f32_e32 v25, v33, v25
	v_mul_f32_e32 v33, 0xbfb8aa3b, v33
	v_mul_f32_e32 v18, v26, v18
	v_mul_f32_e32 v26, 0xbfb8aa3b, v26
	v_mul_f32_e32 v19, v27, v19
	v_mul_f32_e32 v27, 0xbfb8aa3b, v27
	v_mul_f32_e32 v20, v28, v20
	v_mul_f32_e32 v28, 0xbfb8aa3b, v28
	v_mul_f32_e32 v21, v29, v21
	v_mul_f32_e32 v29, 0xbfb8aa3b, v29
	v_exp_f32_e32 v30, v30
	v_exp_f32_e32 v31, v31
	v_exp_f32_e32 v32, v32
	v_exp_f32_e32 v33, v33
	v_exp_f32_e32 v26, v26
	v_exp_f32_e32 v27, v27
	v_exp_f32_e32 v28, v28
	v_exp_f32_e32 v29, v29
	v_add_f32_e32 v30, 1.0, v30
	v_add_f32_e32 v31, 1.0, v31
	v_add_f32_e32 v32, 1.0, v32
	v_add_f32_e32 v33, 1.0, v33
	v_add_f32_e32 v26, 1.0, v26
	v_add_f32_e32 v27, 1.0, v27
	v_add_f32_e32 v28, 1.0, v28
	v_add_f32_e32 v29, 1.0, v29
	v_rcp_f32_e32 v30, v30
	v_rcp_f32_e32 v31, v31
	v_rcp_f32_e32 v32, v32
	v_rcp_f32_e32 v33, v33
	v_rcp_f32_e32 v26, v26
	v_rcp_f32_e32 v27, v27
	v_rcp_f32_e32 v28, v28
	v_rcp_f32_e32 v29, v29
	v_mul_f32_e32 v22, v22, v30
	v_mul_f32_e32 v23, v23, v31
	v_mul_f32_e32 v24, v24, v32
	v_mul_f32_e32 v25, v25, v33
	v_mul_f32_e32 v26, v18, v26
	v_mul_f32_e32 v27, v19, v27
	v_mul_f32_e32 v28, v20, v28
	v_mul_f32_e32 v21, v21, v29
	v_cvt_pkrtz_f16_f32 v18, v22, v23
	v_cvt_pkrtz_f16_f32 v19, v24, v25
	v_cvt_pkrtz_f16_f32 v20, v26, v27
	v_cvt_pkrtz_f16_f32 v21, v28, v21
	global_store_dwordx4 v[36:37], v[18:21], off
	s_nop 1
	v_mov_b32_e32 v18, v198
	v_add_u32_e32 v19, 0xb0, v146
	v_mad_i64_i32 v[20:21], s[8:9], v19, s91, v[114:115]
	v_lshl_add_u64 v[20:21], v[20:21], 0, v[116:117]
	v_pk_mul_f32 v[16:17], v[16:17], v[18:19] op_sel_hi:[1,0]
	v_pk_mul_f32 v[14:15], v[14:15], v[18:19] op_sel_hi:[1,0]
	v_pk_mul_f32 v[12:13], v[12:13], v[18:19] op_sel_hi:[1,0]
	v_pk_mul_f32 v[10:11], v[10:11], v[18:19] op_sel_hi:[1,0]
	v_pk_mul_f32 v[8:9], v[8:9], v[18:19] op_sel_hi:[1,0]
	v_pk_mul_f32 v[6:7], v[6:7], v[18:19] op_sel_hi:[1,0]
	v_pk_mul_f32 v[4:5], v[4:5], v[18:19] op_sel_hi:[1,0]
	v_pk_mul_f32 v[2:3], v[2:3], v[18:19] op_sel_hi:[1,0]
	v_mul_f32_e32 v6, v14, v6
	v_mul_f32_e32 v14, 0xbfb8aa3b, v14
	v_mul_f32_e32 v7, v15, v7
	v_mul_f32_e32 v15, 0xbfb8aa3b, v15
	v_mul_f32_e32 v8, v16, v8
	v_mul_f32_e32 v16, 0xbfb8aa3b, v16
	v_mul_f32_e32 v9, v17, v9
	v_mul_f32_e32 v17, 0xbfb8aa3b, v17
	v_mul_f32_e32 v2, v10, v2
	v_mul_f32_e32 v10, 0xbfb8aa3b, v10
	v_mul_f32_e32 v3, v11, v3
	v_mul_f32_e32 v11, 0xbfb8aa3b, v11
	v_mul_f32_e32 v4, v12, v4
	v_mul_f32_e32 v12, 0xbfb8aa3b, v12
	v_mul_f32_e32 v5, v13, v5
	v_mul_f32_e32 v13, 0xbfb8aa3b, v13
	v_exp_f32_e32 v14, v14
	v_exp_f32_e32 v15, v15
	v_exp_f32_e32 v16, v16
	v_exp_f32_e32 v17, v17
	v_exp_f32_e32 v10, v10
	v_exp_f32_e32 v11, v11
	v_exp_f32_e32 v12, v12
	v_exp_f32_e32 v13, v13
	v_add_f32_e32 v14, 1.0, v14
	v_add_f32_e32 v15, 1.0, v15
	v_add_f32_e32 v16, 1.0, v16
	v_add_f32_e32 v17, 1.0, v17
	v_add_f32_e32 v10, 1.0, v10
	v_add_f32_e32 v11, 1.0, v11
	v_add_f32_e32 v12, 1.0, v12
	v_add_f32_e32 v13, 1.0, v13
	v_rcp_f32_e32 v14, v14
	v_rcp_f32_e32 v15, v15
	v_rcp_f32_e32 v16, v16
	v_rcp_f32_e32 v17, v17
	v_rcp_f32_e32 v10, v10
	v_rcp_f32_e32 v11, v11
	v_rcp_f32_e32 v12, v12
	v_rcp_f32_e32 v13, v13
	v_mul_f32_e32 v6, v6, v14
	v_mul_f32_e32 v7, v7, v15
	v_mul_f32_e32 v8, v8, v16
	v_mul_f32_e32 v9, v9, v17
	v_mul_f32_e32 v10, v2, v10
	v_mul_f32_e32 v11, v3, v11
	v_mul_f32_e32 v12, v4, v12
	v_mul_f32_e32 v5, v5, v13
	v_cvt_pkrtz_f16_f32 v2, v6, v7
	v_cvt_pkrtz_f16_f32 v3, v8, v9
	v_cvt_pkrtz_f16_f32 v4, v10, v11
	v_cvt_pkrtz_f16_f32 v5, v12, v5
	global_store_dwordx4 v[20:21], v[2:5], off
	s_cbranch_vccnz .LBB0_209
	s_andn2_b64 vcc, exec, s[0:1]
	s_cbranch_vccnz .LBB0_208
	s_branch .LBB0_208
